# attention: key rows 256..383 of an item's K tile kept in 16 registers and reused as rows 0..127 of the next item's tile (4 of 12 K loads per thread and item dropped); constants re-materialised after t
# baseline (speedup 1.0000x reference)
.LBB0_1129:
	v_add_co_u32_e32 v20, vcc, s21, v16
	s_not_b32 s63, s14
	s_nop 0
	v_addc_co_u32_e32 v21, vcc, 0, v17, vcc
	v_add_co_u32_e32 v24, vcc, s22, v16
	v_readlane_b32 s10, v254, 49
	s_nop 0
	v_addc_co_u32_e32 v25, vcc, 0, v17, vcc
	v_add_co_u32_e32 v28, vcc, s23, v16
	global_load_dwordx4 v[20:23], v[20:21], off
	s_nop 0
	global_load_dwordx4 v[24:27], v[24:25], off
	v_addc_co_u32_e32 v29, vcc, 0, v17, vcc
	v_add_co_u32_e32 v32, vcc, s24, v16
	s_movk_i32 s14, 0xf0
	s_nop 0
	v_addc_co_u32_e32 v33, vcc, 0, v17, vcc
	v_add_co_u32_e32 v36, vcc, s15, v16
	global_load_dwordx4 v[28:31], v[28:29], off
	s_nop 0
	global_load_dwordx4 v[32:35], v[32:33], off
	v_addc_co_u32_e32 v37, vcc, 0, v17, vcc
	v_add_co_u32_e32 v40, vcc, s18, v16
	v_readlane_b32 s11, v254, 50
	s_nop 0
	v_addc_co_u32_e32 v41, vcc, 0, v17, vcc
	v_add_co_u32_e32 v44, vcc, s19, v16
	global_load_dwordx4 v[36:39], v[36:37], off
	s_nop 0
	global_load_dwordx4 v[40:43], v[40:41], off
	v_addc_co_u32_e32 v45, vcc, 0, v17, vcc
	v_add_co_u32_e32 v16, vcc, s20, v16
	s_and_b64 s[10:11], s[10:11], exec
	s_nop 0
	v_addc_co_u32_e32 v17, vcc, 0, v17, vcc
	global_load_dwordx4 v[44:47], v[44:45], off
	s_nop 0
	global_load_dwordx4 v[48:51], v[16:17], off
	v_xor_b32_e32 v16, v128, v19
	v_lshlrev_b32_e32 v17, 8, v128
	v_lshlrev_b32_e32 v54, 4, v16
	v_and_or_b32 v17, v54, s14, v17
	s_load_dwordx2 s[14:15], s[8:9], 0x70
	s_cselect_b32 s10, 0, 8
	s_lshl_b32 s11, 1, s40
	s_add_u32 s20, s4, s13
	s_addc_u32 s21, s5, 0
	s_waitcnt lgkmcnt(0)
	s_add_u32 s22, s14, 0x1100000
	v_cvt_f32_u32_e32 v152, s11
	s_addc_u32 s23, s15, 0
	s_lshl_b32 s11, s12, 4
	v_and_b32_e32 v149, 63, v19
	s_or_b32 s11, s11, 1
	s_cmp_gt_i32 s28, 0
	v_cmp_gt_u32_e64 s[42:43], 32, v149
	s_cselect_b64 s[24:25], -1, 0
	s_add_i32 s18, s40, 13
	s_and_b64 s[26:27], s[0:1], s[42:43]
	s_cmp_gt_i32 s28, 1
	s_cselect_b64 s[28:29], -1, 0
	s_add_i32 s0, s40, 12
	s_lshl_b64 s[60:61], 1, s0
	v_writelane_b32 v254, s60, 52
	v_bfe_u32 v53, v19, 5, 1
	v_and_b32_e32 v150, 31, v19
	v_writelane_b32 v254, s61, 53
	s_lshl_b64 s[60:61], 2, s0
	v_writelane_b32 v254, s60, 54
	v_ashrrev_i32_e32 v130, 2, v19
	v_lshlrev_b32_e32 v19, 4, v19
	v_lshlrev_b32_e32 v138, 4, v53
	v_writelane_b32 v254, s61, 55
	s_lshl_b64 s[60:61], 3, s0
	v_and_b32_e32 v16, 48, v19
	v_add_u32_e32 v151, 0, v17
	v_lshl_add_u64 v[132:133], s[6:7], 0, v[138:139]
	v_readlane_b32 s6, v253, 56
	v_mov_b32_e32 v17, v139
	v_writelane_b32 v254, s60, 56
	s_waitcnt vmcnt(8)
	ds_write_b128 v151, v[0:3]
	ds_write_b128 v151, v[8:11] offset:8192
	ds_write_b128 v151, v[4:7] offset:16384
	ds_write_b128 v151, v[12:15] offset:24576
	v_or_b32_e32 v2, s6, v150
	v_lshl_add_u64 v[0:1], s[14:15], 0, v[16:17]
	s_mov_b64 s[6:7], 0xc000000
	v_readlane_b32 s1, v253, 51
	v_writelane_b32 v254, s61, 57
	s_lshl_b64 s[60:61], 4, s0
	v_lshl_add_u64 v[134:135], v[0:1], 0, s[6:7]
	v_mov_b32_e32 v0, s1
	s_movk_i32 s1, 0x210
	v_writelane_b32 v254, s60, 58
	v_lshlrev_b32_e32 v52, 3, v18
	v_mad_u32_u24 v4, v150, s1, v0
	v_readlane_b32 s1, v253, 47
	v_writelane_b32 v254, s61, 59
	s_lshl_b64 s[60:61], 5, s0
	s_movk_i32 s50, 0x310
	v_lshl_add_u32 v160, v150, 2, s1
	v_lshlrev_b32_e32 v0, 1, v52
	v_mov_b32_e32 v1, v139
	v_readlane_b32 s1, v253, 53
	v_writelane_b32 v254, s60, 60
	v_mul_lo_u32 v55, v130, s50
	v_lshl_add_u64 v[136:137], s[4:5], 0, v[0:1]
	v_lshl_add_u32 v0, v2, 8, 0
	v_xor_b32_e32 v1, v53, v18
	v_bitop3_b32 v2, v53, v18, 2 bitop3:0x36
	v_bitop3_b32 v5, v53, v18, 4 bitop3:0x36
	v_bitop3_b32 v6, v53, v18, 6 bitop3:0x36
	v_bitop3_b32 v7, v53, v18, 8 bitop3:0x36
	v_bitop3_b32 v8, v53, v18, 10 bitop3:0x36
	v_bitop3_b32 v9, v53, v18, 12 bitop3:0x36
	v_bitop3_b32 v10, v53, v18, 14 bitop3:0x36
	v_add_u32_e32 v12, s1, v138
	v_writelane_b32 v254, s61, 61
	s_lshl_b64 s[60:61], 6, s0
	s_lshl_b64 s[0:1], 7, s0
	v_or_b32_e32 v19, 0x80, v150
	v_lshlrev_b32_e32 v157, 2, v53
	v_add_u32_e32 v3, 0, v55
	v_lshlrev_b32_e32 v1, 4, v1
	v_lshlrev_b32_e32 v2, 4, v2
	v_lshlrev_b32_e32 v5, 4, v5
	v_lshlrev_b32_e32 v6, 4, v6
	v_lshlrev_b32_e32 v7, 4, v7
	v_lshlrev_b32_e32 v8, 4, v8
	v_lshlrev_b32_e32 v9, 4, v9
	v_lshlrev_b32_e32 v10, 4, v10
	s_lshl_b64 s[4:5], 32, s53
	s_lshl_b64 s[12:13], 64, s53
	s_lshl_b64 s[14:15], 0x60, s53
	s_lshl_b64 s[44:45], 0x80, s53
	s_lshl_b64 s[46:47], 0xa0, s53
	s_lshl_b64 s[48:49], 0xc0, s53
	s_lshl_b64 s[72:73], 0xe0, s53
	s_lshl_b64 s[74:75], 0x100, s53
	s_lshl_b64 s[76:77], 0x120, s53
	s_lshl_b64 s[78:79], 0x140, s53
	s_lshl_b64 s[80:81], 0x160, s53
	v_mul_u32_u24_e32 v11, 0x310, v150
	v_mad_u32_u24 v13, v150, s50, v174
	v_writelane_b32 v254, s60, 62
	v_writelane_b32 v255, s0, 0
	s_mov_b32 s51, 0x16000
	v_add_u32_e32 v153, 0x10000, v151
	v_add_u32_e32 v154, 0x12000, v151
	v_add_u32_e32 v155, 0x14000, v151
	v_add_u32_e32 v156, 0x16000, v151
	v_sub_u32_e32 v158, v19, v157
	v_cvt_f32_ubyte0_e32 v159, v157
	v_ashrrev_i32_e32 v131, 31, v130
	s_lshl_b64 s[30:31], 1, s18
	s_lshl_b64 s[54:55], 2, s18
	s_lshl_b64 s[34:35], 3, s18
	s_lshl_b64 s[36:37], 4, s18
	s_lshl_b64 s[38:39], 5, s18
	s_lshl_b64 s[6:7], 6, s18
	s_lshl_b64 s[18:19], 7, s18
	v_writelane_b32 v254, s61, 63
	v_writelane_b32 v255, s1, 1
	s_lshl_b64 s[0:1], 0x2000, s40
	s_lshl_b32 s60, s4, 1
	s_lshl_b32 s64, s12, 1
	s_lshl_b32 s66, s14, 1
	s_lshl_b32 s56, s44, 1
	s_lshl_b32 s68, s46, 1
	s_lshl_b32 s70, s48, 1
	s_lshl_b32 s72, s72, 1
	s_lshl_b32 s74, s74, 1
	s_lshl_b32 s76, s76, 1
	s_lshl_b32 s78, s78, 1
	s_lshl_b32 s80, s80, 1
	v_add_u32_e32 v161, v3, v16
	v_add_u32_e32 v162, v4, v138
	v_add_u32_e32 v163, v0, v1
	v_add_u32_e32 v164, v0, v2
	v_add_u32_e32 v165, v0, v5
	v_add_u32_e32 v166, v0, v6
	v_add_u32_e32 v167, v0, v7
	v_add_u32_e32 v168, v0, v8
	v_add_u32_e32 v169, v0, v9
	v_add_u32_e32 v170, v0, v10
	v_add_u32_e32 v171, v12, v11
	v_add_u32_e32 v191, v12, v13
	s_lshl_b64 s[82:83], 0x4000, s40
	s_lshl_b64 s[84:85], 0x6000, s40
	s_lshl_b64 s[86:87], 0x8000, s40
	s_lshl_b64 s[88:89], 0xa000, s40
	s_lshl_b64 s[90:91], 0xc000, s40
	s_lshl_b64 s[92:93], 0xe000, s40
	s_waitcnt vmcnt(7)
	ds_write_b128 v151, v[20:23] offset:32768
	s_waitcnt vmcnt(6)
	ds_write_b128 v151, v[24:27] offset:40960
	s_waitcnt vmcnt(5)
	ds_write_b128 v151, v[28:31] offset:49152
	s_waitcnt vmcnt(4)
	ds_write_b128 v151, v[32:35] offset:57344
	s_waitcnt vmcnt(3)
	ds_write_b128 v153, v[36:39]
	s_waitcnt vmcnt(2)
	ds_write_b128 v154, v[40:43]
	s_waitcnt vmcnt(1)
	ds_write_b128 v155, v[44:47]
	s_waitcnt vmcnt(0)
	ds_write_b128 v156, v[48:51]
	v_mov_b32_e32 v178, v36
	v_mov_b32_e32 v179, v37
	v_mov_b32_e32 v180, v38
	v_mov_b32_e32 v181, v39
	v_mov_b32_e32 v182, v40
	v_mov_b32_e32 v183, v41
	v_mov_b32_e32 v184, v42
	v_mov_b32_e32 v185, v43
	v_mov_b32_e32 v186, v44
	v_mov_b32_e32 v187, v45
	v_mov_b32_e32 v188, v46
	v_mov_b32_e32 v189, v47
	v_mov_b32_e32 v190, v48
	v_mov_b32_e32 v172, v49
	v_mov_b32_e32 v173, v50
	v_mov_b32_e32 v174, v51
	s_branch .LBB0_1131

.LBB0_1196:
	v_pk_mul_f32 v[48:49], v[140:141], v[48:49] op_sel_hi:[0,1]
	v_pk_mul_f32 v[50:51], v[140:141], v[50:51] op_sel_hi:[0,1]
	v_pk_mul_f32 v[32:33], v[140:141], v[32:33] op_sel_hi:[0,1]
	v_pk_mul_f32 v[34:35], v[140:141], v[34:35] op_sel_hi:[0,1]
	v_pk_mul_f32 v[16:17], v[140:141], v[16:17] op_sel_hi:[0,1]
	v_pk_mul_f32 v[18:19], v[140:141], v[18:19] op_sel_hi:[0,1]
	v_pk_mul_f32 v[0:1], v[140:141], v[0:1] op_sel_hi:[0,1]
	v_pk_mul_f32 v[2:3], v[140:141], v[2:3] op_sel_hi:[0,1]
	s_barrier
	ds_write_b128 v162, v[48:51]
	v_pk_mul_f32 v[48:49], v[140:141], v[52:53] op_sel_hi:[0,1]
	v_pk_mul_f32 v[50:51], v[140:141], v[54:55] op_sel_hi:[0,1]
	ds_write_b128 v162, v[32:35] offset:128
	v_pk_mul_f32 v[32:33], v[140:141], v[36:37] op_sel_hi:[0,1]
	v_pk_mul_f32 v[34:35], v[140:141], v[38:39] op_sel_hi:[0,1]
	ds_write_b128 v162, v[16:19] offset:256
	v_pk_mul_f32 v[16:17], v[140:141], v[20:21] op_sel_hi:[0,1]
	v_pk_mul_f32 v[18:19], v[140:141], v[22:23] op_sel_hi:[0,1]
	ds_write_b128 v162, v[0:3] offset:384
	v_pk_mul_f32 v[0:1], v[140:141], v[4:5] op_sel_hi:[0,1]
	v_pk_mul_f32 v[2:3], v[140:141], v[6:7] op_sel_hi:[0,1]
	ds_write_b128 v162, v[48:51] offset:32
	v_pk_mul_f32 v[48:49], v[140:141], v[56:57] op_sel_hi:[0,1]
	v_pk_mul_f32 v[50:51], v[140:141], v[58:59] op_sel_hi:[0,1]
	ds_write_b128 v162, v[32:35] offset:160
	v_pk_mul_f32 v[32:33], v[140:141], v[40:41] op_sel_hi:[0,1]
	v_pk_mul_f32 v[34:35], v[140:141], v[42:43] op_sel_hi:[0,1]
	ds_write_b128 v162, v[16:19] offset:288
	v_pk_mul_f32 v[16:17], v[140:141], v[24:25] op_sel_hi:[0,1]
	v_pk_mul_f32 v[18:19], v[140:141], v[26:27] op_sel_hi:[0,1]
	ds_write_b128 v162, v[0:3] offset:416
	v_pk_mul_f32 v[0:1], v[140:141], v[8:9] op_sel_hi:[0,1]
	v_pk_mul_f32 v[2:3], v[140:141], v[10:11] op_sel_hi:[0,1]
	ds_write_b128 v162, v[48:51] offset:64
	v_pk_mul_f32 v[48:49], v[140:141], v[60:61] op_sel_hi:[0,1]
	v_pk_mul_f32 v[50:51], v[140:141], v[62:63] op_sel_hi:[0,1]
	ds_write_b128 v162, v[32:35] offset:192
	v_pk_mul_f32 v[32:33], v[140:141], v[44:45] op_sel_hi:[0,1]
	v_pk_mul_f32 v[34:35], v[140:141], v[46:47] op_sel_hi:[0,1]
	ds_write_b128 v162, v[16:19] offset:320
	v_pk_mul_f32 v[16:17], v[140:141], v[28:29] op_sel_hi:[0,1]
	v_pk_mul_f32 v[18:19], v[140:141], v[30:31] op_sel_hi:[0,1]
	ds_write_b128 v162, v[0:3] offset:448
	v_pk_mul_f32 v[0:1], v[140:141], v[12:13] op_sel_hi:[0,1]
	v_pk_mul_f32 v[2:3], v[140:141], v[14:15] op_sel_hi:[0,1]
	ds_write_b128 v162, v[48:51] offset:96
	ds_write_b128 v162, v[32:35] offset:224
	ds_write_b128 v162, v[16:19] offset:352
	ds_write_b128 v162, v[0:3] offset:480
	s_and_saveexec_b64 s[12:13], s[42:43]
	ds_write_b32 v160, v144
	s_or_b64 exec, exec, s[12:13]
	s_waitcnt lgkmcnt(0)
	s_add_i32 s58, s58, 1
	s_cmp_lt_i32 s58, s59
	v_mov_b32_e32 v3, 0
	s_cselect_b64 s[94:95], -1, 0
	s_cmp_ge_i32 s58, s59
	v_mov_b32_e32 v2, 0
	v_mov_b32_e32 v1, 0
	v_mov_b32_e32 v0, 0
	v_mov_b32_e32 v11, 0
	v_mov_b32_e32 v10, 0
	v_mov_b32_e32 v9, 0
	v_mov_b32_e32 v8, 0
	v_mov_b32_e32 v7, 0
	v_mov_b32_e32 v6, 0
	v_mov_b32_e32 v5, 0
	v_mov_b32_e32 v4, 0
	v_mov_b32_e32 v15, 0
	v_mov_b32_e32 v14, 0
	v_mov_b32_e32 v13, 0
	v_mov_b32_e32 v12, 0
	v_mov_b32_e32 v19, 0
	v_mov_b32_e32 v18, 0
	v_mov_b32_e32 v17, 0
	v_mov_b32_e32 v16, 0
	v_mov_b32_e32 v23, 0
	v_mov_b32_e32 v22, 0
	v_mov_b32_e32 v21, 0
	v_mov_b32_e32 v20, 0
	v_mov_b32_e32 v27, 0
	v_mov_b32_e32 v26, 0
	v_mov_b32_e32 v25, 0
	v_mov_b32_e32 v24, 0
	v_mov_b32_e32 v31, 0
	v_mov_b32_e32 v30, 0
	v_mov_b32_e32 v29, 0
	v_mov_b32_e32 v28, 0
	v_mov_b32_e32 v35, 0
	v_mov_b32_e32 v34, 0
	v_mov_b32_e32 v33, 0
	v_mov_b32_e32 v32, 0
	v_mov_b32_e32 v39, 0
	v_mov_b32_e32 v38, 0
	v_mov_b32_e32 v37, 0
	v_mov_b32_e32 v36, 0
	v_mov_b32_e32 v43, 0
	v_mov_b32_e32 v42, 0
	v_mov_b32_e32 v41, 0
	v_mov_b32_e32 v40, 0
	v_mov_b32_e32 v47, 0
	v_mov_b32_e32 v46, 0
	v_mov_b32_e32 v45, 0
	v_mov_b32_e32 v44, 0
	s_cbranch_scc1 .LBB0_1211
	s_and_b32 s5, s58, 63
	s_and_b32 s14, s5, s63
	s_ashr_i32 s4, s58, 6
	s_lshr_b32 s12, s5, s62
	s_lshl_b32 s5, s14, 8
	s_add_i32 s13, s5, 0xffffff80
	s_ashr_i32 s5, s4, 31
	s_lshl_b64 s[4:5], s[4:5], 14
	s_mul_i32 s12, s12, s41
	s_ashr_i32 s15, s13, 31
	s_add_u32 s12, s13, s12
	s_addc_u32 s13, s15, 0
	s_add_u32 s4, s12, s4
	s_addc_u32 s5, s13, s5
	v_lshl_add_u64 v[0:1], s[4:5], 0, v[128:129]
	v_lshlrev_b64 v[0:1], 8, v[0:1]
	s_cmp_lg_u32 s14, 0
	s_cselect_b64 s[12:13], -1, 0
	s_cmp_eq_u32 s14, 0
	v_lshl_add_u64 v[40:41], v[136:137], 0, v[0:1]
	s_cbranch_scc1 .LBB0_1202
	v_mov_b32_e32 v0, v178
	v_mov_b32_e32 v1, v179
	v_mov_b32_e32 v2, v180
	v_mov_b32_e32 v3, v181
	s_branch .LBB0_1203

.LBB0_1203:
	v_cndmask_b32_e64 v5, 0, 1, s[12:13]
	v_mov_b32_e32 v4, 0
	v_cmp_ne_u32_e64 s[48:49], 1, v5
	s_andn2_b64 vcc, exec, s[12:13]
	v_mov_b32_e32 v8, 0
	v_mov_b32_e32 v9, 0
	v_mov_b32_e32 v10, 0
	v_mov_b32_e32 v11, 0
	s_cbranch_vccnz .LBB0_1205
	v_add_co_u32_e32 v6, vcc, 0x2000, v40
	s_nop 1
	v_addc_co_u32_e32 v7, vcc, 0, v41, vcc
	v_mov_b32_e32 v8, v182
	v_mov_b32_e32 v9, v183
	v_mov_b32_e32 v10, v184
	v_mov_b32_e32 v11, v185
.LBB0_1205:
	s_and_b64 vcc, exec, s[48:49]
	v_mov_b32_e32 v5, 0
	v_mov_b32_e32 v6, 0
	v_mov_b32_e32 v7, 0
	s_cbranch_vccnz .LBB0_1207
	v_add_co_u32_e32 v4, vcc, 0x4000, v40
	s_nop 1
	v_addc_co_u32_e32 v5, vcc, 0, v41, vcc
	v_mov_b32_e32 v4, v186
	v_mov_b32_e32 v5, v187
	v_mov_b32_e32 v6, v188
	v_mov_b32_e32 v7, v189
.LBB0_1207:
	s_and_b64 vcc, exec, s[48:49]
	s_cbranch_vccnz .LBB0_1209
	v_add_co_u32_e32 v12, vcc, 0x6000, v40
	s_nop 1
	v_addc_co_u32_e32 v13, vcc, 0, v41, vcc
	v_mov_b32_e32 v12, v190
	v_mov_b32_e32 v13, v172
	v_mov_b32_e32 v14, v173
	v_mov_b32_e32 v15, v174
	s_branch .LBB0_1210

.LBB0_1243:
	s_waitcnt lgkmcnt(1)
	v_cvt_pk_bf16_f32 v52, v52, v53
	v_cvt_pk_bf16_f32 v53, v54, v55
	s_waitcnt lgkmcnt(0)
	v_cvt_pk_bf16_f32 v54, v48, v49
	v_cvt_pk_bf16_f32 v55, v50, v51
	v_lshl_add_u64 v[48:49], s[92:93], 1, v[142:143]
	s_mov_b64 s[12:13], -1
	s_and_b64 vcc, exec, s[94:95]
	global_store_dwordx4 v[48:49], v[52:55], off sc1
	s_barrier
	s_cbranch_vccz .LBB0_1130
	s_waitcnt vmcnt(16)
	ds_write_b128 v151, v[0:3]
	ds_write_b128 v151, v[8:11] offset:8192
	ds_write_b128 v151, v[4:7] offset:16384
	ds_write_b128 v151, v[12:15] offset:24576
	s_waitcnt vmcnt(15)
	ds_write_b128 v151, v[16:19] offset:32768
	s_waitcnt vmcnt(14)
	ds_write_b128 v151, v[20:23] offset:40960
	s_waitcnt vmcnt(13)
	ds_write_b128 v151, v[24:27] offset:49152
	s_waitcnt vmcnt(12)
	ds_write_b128 v151, v[28:31] offset:57344
	s_waitcnt vmcnt(11)
	ds_write_b128 v153, v[32:35]
	s_waitcnt vmcnt(10)
	ds_write_b128 v154, v[36:39]
	s_waitcnt vmcnt(9)
	ds_write_b128 v155, v[40:43]
	s_waitcnt vmcnt(8)
	ds_write_b128 v156, v[44:47]
	v_mov_b32_e32 v178, v32
	v_mov_b32_e32 v179, v33
	v_mov_b32_e32 v180, v34
	v_mov_b32_e32 v181, v35
	v_mov_b32_e32 v182, v36
	v_mov_b32_e32 v183, v37
	v_mov_b32_e32 v184, v38
	v_mov_b32_e32 v185, v39
	v_mov_b32_e32 v186, v40
	v_mov_b32_e32 v187, v41
	v_mov_b32_e32 v188, v42
	v_mov_b32_e32 v189, v43
	v_mov_b32_e32 v190, v44
	v_mov_b32_e32 v172, v45
	v_mov_b32_e32 v173, v46
	v_mov_b32_e32 v174, v47
	s_mov_b64 s[12:13], 0
	s_branch .LBB0_1130
.LBB0_1245:
	v_mov_b32_e32 v172, 0x358637bd
	v_mov_b32_e32 v173, 1
	v_mov_b32_e32 v174, 0x12600
	v_mov_b32_e32 v178, 0x630
	v_mov_b32_e32 v179, 0x840
	v_mov_b32_e32 v180, 0xa50
	v_mov_b32_e32 v181, 0xc60
	v_mov_b32_e32 v182, 0xe70
	v_mov_b32_e32 v183, 0x1080
	v_mov_b32_e32 v184, 0x1290
	v_mov_b32_e32 v185, 0x14a0
	v_mov_b32_e32 v186, 0x16b0
	v_mov_b32_e32 v187, 0x18c0
	v_readlane_b32 s0, v253, 49
	v_readlane_b32 s4, v254, 49
	v_readlane_b32 s1, v253, 50
	v_readlane_b32 s5, v254, 50
	s_or_b64 s[0:1], s[4:5], s[0:1]
	s_waitcnt vmcnt(0)
	v_and_b32_e32 v4, 63, v148
	s_and_b64 vcc, exec, s[0:1]
	v_readlane_b32 s39, v254, 0
	s_mov_b32 s53, 0x20000
	s_mov_b32 s63, 0x10000
	v_readlane_b32 s26, v254, 51
	s_waitcnt lgkmcnt(0)
	s_barrier
	s_cbranch_vccnz .LBB0_1248
	s_load_dwordx2 s[0:1], s[8:9], 0x70
	v_lshlrev_b32_e32 v0, 3, v4
	v_and_b32_e32 v0, 56, v0
	v_lshrrev_b32_e32 v5, 5, v4
	v_and_b32_e32 v2, 31, v148
	v_readlane_b32 s4, v253, 52
	v_lshrrev_b32_e32 v6, 3, v4
	v_lshlrev_b32_e32 v138, 1, v0
	v_lshl_add_u32 v3, v2, 2, s4
	v_mul_u32_u24_e32 v11, 0x84, v5
	v_mul_u32_u24_e32 v7, 0x84, v0
	s_waitcnt lgkmcnt(0)
	v_lshl_add_u64 v[0:1], s[0:1], 0, v[138:139]
	s_mov_b64 s[0:1], 0x1200000
	v_lshlrev_b32_e32 v8, 2, v6
	v_lshl_add_u64 v[0:1], v[0:1], 0, s[0:1]
	v_add3_u32 v7, s4, v7, v8
	v_or_b32_e32 v8, 8, v6
	v_or_b32_e32 v9, 16, v6
	v_or_b32_e32 v10, 24, v6
	v_lshlrev_b32_e32 v138, 2, v2
	v_add_u32_e32 v11, v3, v11
	v_readlane_b32 s4, v253, 57
	v_readlane_b32 s5, v253, 54
	v_readlane_b32 s6, v253, 48
	v_readlane_b32 s12, v253, 55
	v_readlane_b32 s13, v253, 58
	s_mov_b32 s14, 0x12000
	s_mov_b32 s15, 0x14000
	s_mov_b32 s18, 0x16000
	s_mov_b32 s19, 0x8000
	s_mov_b32 s20, 0xa000
	s_mov_b32 s21, 0xc000
	s_mov_b32 s22, 0xe000
	s_mov_b32 s23, 0x30000
